# S loop control from registers: union list and selection masks kept in VGPR lanes and read with v_readlane, tile addresses in SGPRs (saddr loads), plain f32 VALU in the softmax
# speedup vs baseline: 1.0297x; 1.0067x over previous
.LBB0_2164:
	s_or_b64 exec, exec, s[20:21]
	v_add_u32_e32 v38, v34, v35
	v_bcnt_u32_b32 v37, v37, 0
	v_add_u32_e32 v38, v38, v36
	v_add_u32_e32 v150, v38, v37
	v_mul_f32_e32 v38, v133, v146
	v_cmp_eq_u32_e32 vcc, 0, v150
	v_pk_mul_f32 v[82:83], v[38:39], v[18:19] op_sel_hi:[0,1]
	v_add_u32_e32 v215, 0x9000, v214
	v_pk_mul_f32 v[84:85], v[38:39], v[20:21] op_sel_hi:[0,1]
	v_add_u32_e32 v216, 0x9008, v214
	v_pk_mul_f32 v[86:87], v[38:39], v[22:23] op_sel_hi:[0,1]
	v_add_u32_e32 v217, 0x9020, v214
	v_pk_mul_f32 v[88:89], v[38:39], v[24:25] op_sel_hi:[0,1]
	v_add_u32_e32 v218, 0x9028, v214
	v_pk_mul_f32 v[90:91], v[38:39], v[26:27] op_sel_hi:[0,1]
	v_add_u32_e32 v219, 0x9040, v214
	v_pk_mul_f32 v[92:93], v[38:39], v[28:29] op_sel_hi:[0,1]
	v_add_u32_e32 v220, 0x9048, v214
	v_pk_mul_f32 v[94:95], v[38:39], v[30:31] op_sel_hi:[0,1]
	v_add_u32_e32 v221, 0x9060, v214
	v_pk_mul_f32 v[96:97], v[38:39], v[32:33] op_sel_hi:[0,1]
	v_add_u32_e32 v222, 0x9068, v214
	v_pk_mul_f32 v[134:135], v[38:39], v[2:3] op_sel_hi:[0,1]
	v_add_u32_e32 v223, 0x9080, v214
	v_pk_mul_f32 v[136:137], v[38:39], v[4:5] op_sel_hi:[0,1]
	v_add_u32_e32 v224, 0x9088, v214
	v_pk_mul_f32 v[138:139], v[38:39], v[6:7] op_sel_hi:[0,1]
	v_add_u32_e32 v225, 0x90a0, v214
	v_pk_mul_f32 v[140:141], v[38:39], v[8:9] op_sel_hi:[0,1]
	v_add_u32_e32 v226, 0x90a8, v214
	v_pk_mul_f32 v[142:143], v[38:39], v[10:11] op_sel_hi:[0,1]
	v_add_u32_e32 v227, 0x90c0, v214
	v_pk_mul_f32 v[144:145], v[38:39], v[12:13] op_sel_hi:[0,1]
	v_add_u32_e32 v228, 0x90c8, v214
	v_pk_mul_f32 v[146:147], v[38:39], v[14:15] op_sel_hi:[0,1]
	v_add_u32_e32 v229, 0x90e0, v214
	v_pk_mul_f32 v[148:149], v[38:39], v[16:17] op_sel_hi:[0,1]
	v_add_u32_e32 v230, 0x90e8, v214
	s_and_b64 vcc, exec, vcc
	s_lshl_b32 s24, s71, 19
	s_waitcnt lgkmcnt(0)
	s_barrier
	ds_write2_b32 v215, v82, v83 offset1:1
	ds_write2_b32 v216, v84, v85 offset1:1
	ds_write2_b32 v217, v86, v87 offset1:1
	ds_write2_b32 v218, v88, v89 offset1:1
	ds_write2_b32 v219, v90, v91 offset1:1
	ds_write2_b32 v220, v92, v93 offset1:1
	ds_write2_b32 v221, v94, v95 offset1:1
	ds_write2_b32 v222, v96, v97 offset1:1
	ds_write2_b32 v223, v134, v135 offset1:1
	ds_write2_b32 v224, v136, v137 offset1:1
	ds_write2_b32 v225, v138, v139 offset1:1
	ds_write2_b32 v226, v140, v141 offset1:1
	ds_write2_b32 v227, v142, v143 offset1:1
	ds_write2_b32 v228, v144, v145 offset1:1
	ds_write2_b32 v229, v146, v147 offset1:1
	ds_write2_b32 v230, v148, v149 offset1:1
	s_cbranch_vccnz .LBB0_2181
	s_lshl_b32 s96, s66, 12
	s_and_b32 s96, s96, 0x6000
	s_lshl_b32 s95, s66, 3
	s_and_b32 s95, s95, 8
	s_sub_i32 s94, 0x1ff0, s70
	s_mov_b32 s86, 0xff00ff00
	s_mov_b32 s87, 0xff00ff00
	s_mov_b32 s30, 0x00ff00ff
	s_mov_b32 s31, 0x00ff00ff
	s_mov_b32 s98, 0x1000
	s_mov_b32 s99, 0
	v_and_b32_e32 v40, 15, v166
	v_bfe_u32 v41, v166, 4, 2
	v_lshrrev_b32_e32 v42, 6, v166
	v_lshlrev_b32_e32 v36, 4, v42
	v_and_b32_e32 v37, 63, v166
	v_readfirstlane_b32 s97, v36
	v_lshlrev_b32_e32 v37, 2, v37
	v_add_u32_e32 v37, 0x11200, v37
	ds_read_b32 v149, v37
	ds_read_b32 v133, v37 offset:256
	ds_read_b32 v148, v37 offset:512
	v_mul_u32_u24_e32 v234, 0x90, v40
	v_lshl_add_u32 v234, v41, 4, v234
	v_bfe_u32 v43, v166, 3, 1
	v_lshl_add_u32 v43, v42, 2, v43
	v_add_u32_e32 v236, s94, v43
	v_lshlrev_b32_e32 v44, 2, v41
	v_sub_u32_e32 v239, v236, v44
	v_lshl_add_u32 v45, v42, 5, v40
	v_mul_u32_u24_e32 v45, 0x41, v45
	v_lshl_add_u32 v45, v41, 2, v45
	v_lshlrev_b32_e32 v45, 2, v45
	v_add_u32_e32 v237, 0x9000, v45
	v_add_u32_e32 v238, 0x1040, v237
	v_add_u32_e32 v46, s96, v236
	v_mov_b32_e32 v47, 0
	v_lshlrev_b64 v[46:47], 11, v[46:47]
	v_lshl_add_u64 v[46:47], s[42:43], 0, v[46:47]
	v_and_b32_e32 v48, 7, v166
	v_or_b32_e32 v48, s95, v48
	v_lshlrev_b32_e32 v48, 7, v48
	v_lshl_add_u32 v48, v41, 4, v48
	v_mov_b32_e32 v49, 0
	v_lshl_add_u64 v[46:47], v[46:47], 0, v[48:49]
	global_load_dwordx4 v[66:69], v[46:47], off
	global_load_dwordx4 v[70:73], v[46:47], off offset:64
	v_lshl_add_u64 v[48:49], v[46:47], 0, s[98:99]
	global_load_dwordx4 v[74:77], v[48:49], off
	global_load_dwordx4 v[78:81], v[48:49], off offset:64
	v_mov_b32_e32 v235, 0
	s_lshl_b32 s22, s24, 1
	v_readlane_b32 s20, v231, 14
	s_add_u32 s20, s20, s22
	v_readlane_b32 s21, v231, 10
	s_addc_u32 s21, s21, 0
	s_add_u32 s22, s52, s22
	s_addc_u32 s23, s53, 0
	v_add_u32_e32 v134, v128, v106
	v_add_u32_e32 v135, v128, v108
	v_readfirstlane_b32 s101, v150
	s_mov_b32 s25, 0
	s_waitcnt lgkmcnt(0)
	s_and_b32 s38, s25, 63
	v_readlane_b32 s32, v133, s38
	v_readlane_b32 s38, v148, s38
	s_bitcmp1_b32 s25, 6
	s_cselect_b32 s32, s38, s32
	s_lshl_b32 s32, s32, 13
	s_add_u32 s28, s20, s32
	s_addc_u32 s29, s21, 0
	s_add_u32 s82, s22, s32
	s_addc_u32 s83, s23, 0
	global_load_dwordx4 v[82:85], v134, s[28:29]
	global_load_dwordx4 v[86:89], v134, s[82:83]
	global_load_dwordx4 v[90:93], v135, s[28:29]
	global_load_dwordx4 v[94:97], v135, s[82:83]
	s_cmp_lt_u32 s101, 2
	s_cbranch_scc1 .Lsb16_pa
	s_mov_b32 s58, 1
	s_and_b32 s38, s58, 63
	v_readlane_b32 s32, v133, s38
	v_readlane_b32 s38, v148, s38
	s_bitcmp1_b32 s58, 6
	s_cselect_b32 s32, s38, s32
	s_lshl_b32 s32, s32, 13
	s_add_u32 s28, s20, s32
	s_addc_u32 s29, s21, 0
	s_add_u32 s82, s22, s32
	s_addc_u32 s83, s23, 0
	global_load_dwordx4 v[240:243], v134, s[28:29]
	global_load_dwordx4 v[244:247], v134, s[82:83]
	global_load_dwordx4 v[248:251], v135, s[28:29]
	global_load_dwordx4 v[252:255], v135, s[82:83]
	s_waitcnt vmcnt(4)
	s_branch .Lsb16_pb

.Lsb16_pb:
	ds_write_b128 v153, v[82:85]
	ds_write_b128 v153, v[86:89] offset:9216
	ds_write_b128 v155, v[90:93]
	ds_write_b128 v155, v[94:97] offset:9216
	s_cmp_lt_u32 s101, 3
	s_cbranch_scc1 .Lsb16_pc
	s_mov_b32 s58, 2
	s_and_b32 s38, s58, 63
	v_readlane_b32 s32, v133, s38
	v_readlane_b32 s38, v148, s38
	s_bitcmp1_b32 s58, 6
	s_cselect_b32 s32, s38, s32
	s_lshl_b32 s32, s32, 13
	s_add_u32 s28, s20, s32
	s_addc_u32 s29, s21, 0
	s_add_u32 s82, s22, s32
	s_addc_u32 s83, s23, 0
	global_load_dwordx4 v[82:85], v134, s[28:29]
	global_load_dwordx4 v[86:89], v134, s[82:83]
	global_load_dwordx4 v[90:93], v135, s[28:29]
	global_load_dwordx4 v[94:97], v135, s[82:83]

.Lsb16_step_0:
	s_add_i32 s58, s25, 1
	s_cmp_ge_u32 s58, s101
	s_cbranch_scc1 .Lsb16_nost_0
	s_add_i32 s58, s25, 2
	s_cmp_ge_u32 s58, s101
	s_cbranch_scc1 .Lsb16_w0_0
	s_waitcnt vmcnt(4)
	s_branch .Lsb16_wr_0

.Lsb16_wr_0:
	ds_write_b128 v153, v[240:243] offset:18432
	ds_write_b128 v153, v[244:247] offset:27648
	ds_write_b128 v155, v[248:251] offset:18432
	ds_write_b128 v155, v[252:255] offset:27648
	s_add_i32 s58, s25, 3
	s_cmp_ge_u32 s58, s101
	s_cbranch_scc1 .Lsb16_nost_0
	s_and_b32 s38, s58, 63
	v_readlane_b32 s32, v133, s38
	v_readlane_b32 s38, v148, s38
	s_bitcmp1_b32 s58, 6
	s_cselect_b32 s32, s38, s32
	s_lshl_b32 s32, s32, 13
	s_add_u32 s28, s20, s32
	s_addc_u32 s29, s21, 0
	s_add_u32 s82, s22, s32
	s_addc_u32 s83, s23, 0
	global_load_dwordx4 v[240:243], v134, s[28:29]
	global_load_dwordx4 v[244:247], v134, s[82:83]
	global_load_dwordx4 v[248:251], v135, s[28:29]
	global_load_dwordx4 v[252:255], v135, s[82:83]
.Lsb16_nost_0:
	s_and_b32 s38, s25, 63
	v_readlane_b32 s32, v133, s38
	v_readlane_b32 s38, v148, s38
	s_bitcmp1_b32 s25, 6
	s_cselect_b32 s76, s38, s32
	s_lshr_b32 s77, s76, 5
	s_add_i32 s77, s77, s97
	s_and_b32 s78, s76, 31
	v_readlane_b32 s79, v149, s77
	s_add_i32 s77, s77, 4
	v_readlane_b32 s80, v149, s77
	s_add_i32 s77, s77, 4
	v_readlane_b32 s81, v149, s77
	s_add_i32 s77, s77, 4
	v_readlane_b32 s82, v149, s77
	s_bitcmp1_b32 s79, s78
	s_cselect_b64 s[56:57], s[30:31], 0
	s_bitcmp1_b32 s80, s78
	s_cselect_b64 s[28:29], s[86:87], 0
	s_or_b64 s[56:57], s[56:57], s[28:29]
	s_bitcmp1_b32 s81, s78
	s_cselect_b64 s[98:99], s[30:31], 0
	s_bitcmp1_b32 s82, s78
	s_cselect_b64 s[28:29], s[86:87], 0
	s_or_b64 s[98:99], s[98:99], s[28:29]
	s_or_b64 s[28:29], s[56:57], s[98:99]
	s_cmp_eq_u64 s[28:29], 0
	s_cbranch_scc1 .Lsb16_end_0
	s_lshl_b32 s83, s76, 6
	v_subrev_u32_e32 v147, s83, v239
	s_cmp_eq_u64 s[56:57], 0
	s_cbranch_scc1 .Lsb16_g1_0
	ds_read_b128 v[50:53], v234
	ds_read_b128 v[54:57], v234 offset:64
	ds_read_b128 v[58:61], v234 offset:2304
	ds_read_b128 v[62:65], v234 offset:2368
	v_cndmask_b32_e64 v146, v213, v100, s[56:57]
	s_waitcnt lgkmcnt(3)
	v_mfma_f32_16x16x32_bf16 v[34:37], v[50:53], v[66:69], 0
	s_waitcnt lgkmcnt(2)
	v_mfma_f32_16x16x32_bf16 v[34:37], v[54:57], v[70:73], v[34:37]
	ds_read_b128 v[50:53], v234 offset:4608
	ds_read_b128 v[54:57], v234 offset:4672
	s_waitcnt lgkmcnt(3)
	v_mfma_f32_16x16x32_bf16 v[38:41], v[58:61], v[66:69], 0
	s_waitcnt lgkmcnt(2)
	v_mfma_f32_16x16x32_bf16 v[38:41], v[62:65], v[70:73], v[38:41]
	ds_read_b128 v[58:61], v234 offset:6912
	ds_read_b128 v[62:65], v234 offset:6976
	s_waitcnt lgkmcnt(3)
	v_mfma_f32_16x16x32_bf16 v[42:45], v[50:53], v[66:69], 0
	s_waitcnt lgkmcnt(2)
	v_mfma_f32_16x16x32_bf16 v[42:45], v[54:57], v[70:73], v[42:45]
	s_waitcnt lgkmcnt(1)
	v_mfma_f32_16x16x32_bf16 v[46:49], v[58:61], v[66:69], 0
	s_waitcnt lgkmcnt(0)
	v_mfma_f32_16x16x32_bf16 v[46:49], v[62:65], v[70:73], v[46:49]
	ds_read_b128 v[50:53], v234 offset:9216
	ds_read_b128 v[54:57], v234 offset:9280
	ds_read_b128 v[58:61], v234 offset:11520
	ds_read_b128 v[62:65], v234 offset:11584
	v_fma_f32 v34, v34, s48, v146
	v_fma_f32 v35, v35, s48, v146
	v_fma_f32 v36, v36, s48, v146
	v_fma_f32 v37, v37, s48, v146
	v_fma_f32 v38, v38, s48, v146
	v_fma_f32 v39, v39, s48, v146
	v_fma_f32 v40, v40, s48, v146
	v_fma_f32 v41, v41, s48, v146
	v_fma_f32 v42, v42, s48, v146
	v_fma_f32 v43, v43, s48, v146
	v_fma_f32 v44, v44, s48, v146
	v_fma_f32 v45, v45, s48, v146
	v_fma_f32 v46, v46, s48, v146
	v_fma_f32 v47, v47, s48, v146
	v_fma_f32 v48, v48, s48, v146
	v_fma_f32 v49, v49, s48, v146
	s_cmp_lg_u32 s76, s72
	s_cbranch_scc1 .Lsb16_nm0_0
	v_cmp_le_i32_e64 s[28:29], 0, v147
	s_nop 1
	v_cndmask_b32_e64 v34, v213, v34, s[28:29]
	v_cmp_le_i32_e64 s[28:29], 1, v147
	s_nop 1
	v_cndmask_b32_e64 v35, v213, v35, s[28:29]
	v_cmp_le_i32_e64 s[28:29], 2, v147
	s_nop 1
	v_cndmask_b32_e64 v36, v213, v36, s[28:29]
	v_cmp_le_i32_e64 s[28:29], 3, v147
	s_nop 1
	v_cndmask_b32_e64 v37, v213, v37, s[28:29]
	v_cmp_le_i32_e64 s[28:29], 16, v147
	s_nop 1
	v_cndmask_b32_e64 v38, v213, v38, s[28:29]
	v_cmp_le_i32_e64 s[28:29], 17, v147
	s_nop 1
	v_cndmask_b32_e64 v39, v213, v39, s[28:29]
	v_cmp_le_i32_e64 s[28:29], 18, v147
	s_nop 1
	v_cndmask_b32_e64 v40, v213, v40, s[28:29]
	v_cmp_le_i32_e64 s[28:29], 19, v147
	s_nop 1
	v_cndmask_b32_e64 v41, v213, v41, s[28:29]
	v_cmp_le_i32_e64 s[28:29], 32, v147
	s_nop 1
	v_cndmask_b32_e64 v42, v213, v42, s[28:29]
	v_cmp_le_i32_e64 s[28:29], 33, v147
	s_nop 1
	v_cndmask_b32_e64 v43, v213, v43, s[28:29]
	v_cmp_le_i32_e64 s[28:29], 34, v147
	s_nop 1
	v_cndmask_b32_e64 v44, v213, v44, s[28:29]
	v_cmp_le_i32_e64 s[28:29], 35, v147
	s_nop 1
	v_cndmask_b32_e64 v45, v213, v45, s[28:29]
	v_cmp_le_i32_e64 s[28:29], 48, v147
	s_nop 1
	v_cndmask_b32_e64 v46, v213, v46, s[28:29]
	v_cmp_le_i32_e64 s[28:29], 49, v147
	s_nop 1
	v_cndmask_b32_e64 v47, v213, v47, s[28:29]
	v_cmp_le_i32_e64 s[28:29], 50, v147
	s_nop 1
	v_cndmask_b32_e64 v48, v213, v48, s[28:29]
	v_cmp_le_i32_e64 s[28:29], 51, v147
	s_nop 1
	v_cndmask_b32_e64 v49, v213, v49, s[28:29]
.Lsb16_nm0_0:
	v_exp_f32_e32 v34, v34
	v_exp_f32_e32 v35, v35
	v_exp_f32_e32 v36, v36
	v_exp_f32_e32 v37, v37
	v_exp_f32_e32 v38, v38
	v_exp_f32_e32 v39, v39
	v_exp_f32_e32 v40, v40
	v_exp_f32_e32 v41, v41
	v_exp_f32_e32 v42, v42
	v_exp_f32_e32 v43, v43
	v_exp_f32_e32 v44, v44
	v_exp_f32_e32 v45, v45
	v_exp_f32_e32 v46, v46
	v_exp_f32_e32 v47, v47
	v_exp_f32_e32 v48, v48
	v_exp_f32_e32 v49, v49
	v_add_f32_e32 v138, v34, v35
	v_add_f32_e32 v139, v36, v37
	v_add_f32_e32 v140, v38, v39
	v_add_f32_e32 v141, v40, v41
	v_add_f32_e32 v138, v138, v42
	v_add_f32_e32 v139, v139, v43
	v_add_f32_e32 v140, v140, v44
	v_add_f32_e32 v141, v141, v45
	v_add_f32_e32 v138, v138, v46
	v_add_f32_e32 v139, v139, v47
	v_add_f32_e32 v140, v140, v48
	v_add_f32_e32 v141, v141, v49
	v_add_f32_e32 v138, v138, v139
	v_add_f32_e32 v140, v140, v141
	v_add_f32_e32 v138, v138, v140
	v_add_f32_e32 v129, v129, v138
	v_cvt_pk_bf16_f32 v138, v34, v35
	v_cvt_pk_bf16_f32 v139, v36, v37
	v_cvt_pk_bf16_f32 v140, v38, v39
	v_cvt_pk_bf16_f32 v141, v40, v41
	v_cvt_pk_bf16_f32 v142, v42, v43
	v_cvt_pk_bf16_f32 v143, v44, v45
	v_cvt_pk_bf16_f32 v144, v46, v47
	v_cvt_pk_bf16_f32 v145, v48, v49
	s_waitcnt lgkmcnt(3)
	v_mfma_f32_16x16x32_bf16 v[2:5], v[50:53], v[138:141], v[2:5]
	s_waitcnt lgkmcnt(2)
	v_mfma_f32_16x16x32_bf16 v[2:5], v[54:57], v[142:145], v[2:5]
	ds_read_b128 v[50:53], v234 offset:13824
	ds_read_b128 v[54:57], v234 offset:13888
	s_waitcnt lgkmcnt(3)
	v_mfma_f32_16x16x32_bf16 v[6:9], v[58:61], v[138:141], v[6:9]
	s_waitcnt lgkmcnt(2)
	v_mfma_f32_16x16x32_bf16 v[6:9], v[62:65], v[142:145], v[6:9]
	ds_read_b128 v[58:61], v234 offset:16128
	ds_read_b128 v[62:65], v234 offset:16192
	s_waitcnt lgkmcnt(3)
	v_mfma_f32_16x16x32_bf16 v[10:13], v[50:53], v[138:141], v[10:13]
	s_waitcnt lgkmcnt(2)
	v_mfma_f32_16x16x32_bf16 v[10:13], v[54:57], v[142:145], v[10:13]
	s_waitcnt lgkmcnt(1)
	v_mfma_f32_16x16x32_bf16 v[14:17], v[58:61], v[138:141], v[14:17]
	s_waitcnt lgkmcnt(0)
	v_mfma_f32_16x16x32_bf16 v[14:17], v[62:65], v[142:145], v[14:17]
.Lsb16_g1_0:
	s_cmp_eq_u64 s[98:99], 0
	s_cbranch_scc1 .Lsb16_end_0
	ds_read_b128 v[50:53], v234
	ds_read_b128 v[54:57], v234 offset:64
	ds_read_b128 v[58:61], v234 offset:2304
	ds_read_b128 v[62:65], v234 offset:2368
	v_cndmask_b32_e64 v146, v213, v100, s[98:99]
	v_add_u32_e32 v147, 2, v147
	s_waitcnt lgkmcnt(3)
	v_mfma_f32_16x16x32_bf16 v[34:37], v[50:53], v[74:77], 0
	s_waitcnt lgkmcnt(2)
	v_mfma_f32_16x16x32_bf16 v[34:37], v[54:57], v[78:81], v[34:37]
	ds_read_b128 v[50:53], v234 offset:4608
	ds_read_b128 v[54:57], v234 offset:4672
	s_waitcnt lgkmcnt(3)
	v_mfma_f32_16x16x32_bf16 v[38:41], v[58:61], v[74:77], 0
	s_waitcnt lgkmcnt(2)
	v_mfma_f32_16x16x32_bf16 v[38:41], v[62:65], v[78:81], v[38:41]
	ds_read_b128 v[58:61], v234 offset:6912
	ds_read_b128 v[62:65], v234 offset:6976
	s_waitcnt lgkmcnt(3)
	v_mfma_f32_16x16x32_bf16 v[42:45], v[50:53], v[74:77], 0
	s_waitcnt lgkmcnt(2)
	v_mfma_f32_16x16x32_bf16 v[42:45], v[54:57], v[78:81], v[42:45]
	s_waitcnt lgkmcnt(1)
	v_mfma_f32_16x16x32_bf16 v[46:49], v[58:61], v[74:77], 0
	s_waitcnt lgkmcnt(0)
	v_mfma_f32_16x16x32_bf16 v[46:49], v[62:65], v[78:81], v[46:49]
	ds_read_b128 v[50:53], v234 offset:9216
	ds_read_b128 v[54:57], v234 offset:9280
	ds_read_b128 v[58:61], v234 offset:11520
	ds_read_b128 v[62:65], v234 offset:11584
	v_fma_f32 v34, v34, s48, v146
	v_fma_f32 v35, v35, s48, v146
	v_fma_f32 v36, v36, s48, v146
	v_fma_f32 v37, v37, s48, v146
	v_fma_f32 v38, v38, s48, v146
	v_fma_f32 v39, v39, s48, v146
	v_fma_f32 v40, v40, s48, v146
	v_fma_f32 v41, v41, s48, v146
	v_fma_f32 v42, v42, s48, v146
	v_fma_f32 v43, v43, s48, v146
	v_fma_f32 v44, v44, s48, v146
	v_fma_f32 v45, v45, s48, v146
	v_fma_f32 v46, v46, s48, v146
	v_fma_f32 v47, v47, s48, v146
	v_fma_f32 v48, v48, s48, v146
	v_fma_f32 v49, v49, s48, v146
	s_cmp_lg_u32 s76, s72
	s_cbranch_scc1 .Lsb16_nm1_0
	v_cmp_le_i32_e64 s[28:29], 0, v147
	s_nop 1
	v_cndmask_b32_e64 v34, v213, v34, s[28:29]
	v_cmp_le_i32_e64 s[28:29], 1, v147
	s_nop 1
	v_cndmask_b32_e64 v35, v213, v35, s[28:29]
	v_cmp_le_i32_e64 s[28:29], 2, v147
	s_nop 1
	v_cndmask_b32_e64 v36, v213, v36, s[28:29]
	v_cmp_le_i32_e64 s[28:29], 3, v147
	s_nop 1
	v_cndmask_b32_e64 v37, v213, v37, s[28:29]
	v_cmp_le_i32_e64 s[28:29], 16, v147
	s_nop 1
	v_cndmask_b32_e64 v38, v213, v38, s[28:29]
	v_cmp_le_i32_e64 s[28:29], 17, v147
	s_nop 1
	v_cndmask_b32_e64 v39, v213, v39, s[28:29]
	v_cmp_le_i32_e64 s[28:29], 18, v147
	s_nop 1
	v_cndmask_b32_e64 v40, v213, v40, s[28:29]
	v_cmp_le_i32_e64 s[28:29], 19, v147
	s_nop 1
	v_cndmask_b32_e64 v41, v213, v41, s[28:29]
	v_cmp_le_i32_e64 s[28:29], 32, v147
	s_nop 1
	v_cndmask_b32_e64 v42, v213, v42, s[28:29]
	v_cmp_le_i32_e64 s[28:29], 33, v147
	s_nop 1
	v_cndmask_b32_e64 v43, v213, v43, s[28:29]
	v_cmp_le_i32_e64 s[28:29], 34, v147
	s_nop 1
	v_cndmask_b32_e64 v44, v213, v44, s[28:29]
	v_cmp_le_i32_e64 s[28:29], 35, v147
	s_nop 1
	v_cndmask_b32_e64 v45, v213, v45, s[28:29]
	v_cmp_le_i32_e64 s[28:29], 48, v147
	s_nop 1
	v_cndmask_b32_e64 v46, v213, v46, s[28:29]
	v_cmp_le_i32_e64 s[28:29], 49, v147
	s_nop 1
	v_cndmask_b32_e64 v47, v213, v47, s[28:29]
	v_cmp_le_i32_e64 s[28:29], 50, v147
	s_nop 1
	v_cndmask_b32_e64 v48, v213, v48, s[28:29]
	v_cmp_le_i32_e64 s[28:29], 51, v147
	s_nop 1
	v_cndmask_b32_e64 v49, v213, v49, s[28:29]
.Lsb16_nm1_0:
	v_exp_f32_e32 v34, v34
	v_exp_f32_e32 v35, v35
	v_exp_f32_e32 v36, v36
	v_exp_f32_e32 v37, v37
	v_exp_f32_e32 v38, v38
	v_exp_f32_e32 v39, v39
	v_exp_f32_e32 v40, v40
	v_exp_f32_e32 v41, v41
	v_exp_f32_e32 v42, v42
	v_exp_f32_e32 v43, v43
	v_exp_f32_e32 v44, v44
	v_exp_f32_e32 v45, v45
	v_exp_f32_e32 v46, v46
	v_exp_f32_e32 v47, v47
	v_exp_f32_e32 v48, v48
	v_exp_f32_e32 v49, v49
	v_add_f32_e32 v138, v34, v35
	v_add_f32_e32 v139, v36, v37
	v_add_f32_e32 v140, v38, v39
	v_add_f32_e32 v141, v40, v41
	v_add_f32_e32 v138, v138, v42
	v_add_f32_e32 v139, v139, v43
	v_add_f32_e32 v140, v140, v44
	v_add_f32_e32 v141, v141, v45
	v_add_f32_e32 v138, v138, v46
	v_add_f32_e32 v139, v139, v47
	v_add_f32_e32 v140, v140, v48
	v_add_f32_e32 v141, v141, v49
	v_add_f32_e32 v138, v138, v139
	v_add_f32_e32 v140, v140, v141
	v_add_f32_e32 v138, v138, v140
	v_add_f32_e32 v235, v235, v138
	v_cvt_pk_bf16_f32 v138, v34, v35
	v_cvt_pk_bf16_f32 v139, v36, v37
	v_cvt_pk_bf16_f32 v140, v38, v39
	v_cvt_pk_bf16_f32 v141, v40, v41
	v_cvt_pk_bf16_f32 v142, v42, v43
	v_cvt_pk_bf16_f32 v143, v44, v45
	v_cvt_pk_bf16_f32 v144, v46, v47
	v_cvt_pk_bf16_f32 v145, v48, v49
	s_waitcnt lgkmcnt(3)
	v_mfma_f32_16x16x32_bf16 v[18:21], v[50:53], v[138:141], v[18:21]
	s_waitcnt lgkmcnt(2)
	v_mfma_f32_16x16x32_bf16 v[18:21], v[54:57], v[142:145], v[18:21]
	ds_read_b128 v[50:53], v234 offset:13824
	ds_read_b128 v[54:57], v234 offset:13888
	s_waitcnt lgkmcnt(3)
	v_mfma_f32_16x16x32_bf16 v[22:25], v[58:61], v[138:141], v[22:25]
	s_waitcnt lgkmcnt(2)
	v_mfma_f32_16x16x32_bf16 v[22:25], v[62:65], v[142:145], v[22:25]
	ds_read_b128 v[58:61], v234 offset:16128
	ds_read_b128 v[62:65], v234 offset:16192
	s_waitcnt lgkmcnt(3)
	v_mfma_f32_16x16x32_bf16 v[26:29], v[50:53], v[138:141], v[26:29]
	s_waitcnt lgkmcnt(2)
	v_mfma_f32_16x16x32_bf16 v[26:29], v[54:57], v[142:145], v[26:29]
	s_waitcnt lgkmcnt(1)
	v_mfma_f32_16x16x32_bf16 v[30:33], v[58:61], v[138:141], v[30:33]
	s_waitcnt lgkmcnt(0)
	v_mfma_f32_16x16x32_bf16 v[30:33], v[62:65], v[142:145], v[30:33]
.Lsb16_end_0:
	s_add_i32 s25, s25, 1
	s_cmp_eq_u32 s25, s101
	s_waitcnt lgkmcnt(0)
	s_barrier
	s_cbranch_scc1 .LBB0_2180

.Lsb16_wr_1:
	ds_write_b128 v153, v[82:85]
	ds_write_b128 v153, v[86:89] offset:9216
	ds_write_b128 v155, v[90:93]
	ds_write_b128 v155, v[94:97] offset:9216
	s_add_i32 s58, s25, 3
	s_cmp_ge_u32 s58, s101
	s_cbranch_scc1 .Lsb16_nost_1
	s_and_b32 s38, s58, 63
	v_readlane_b32 s32, v133, s38
	v_readlane_b32 s38, v148, s38
	s_bitcmp1_b32 s58, 6
	s_cselect_b32 s32, s38, s32
	s_lshl_b32 s32, s32, 13
	s_add_u32 s28, s20, s32
	s_addc_u32 s29, s21, 0
	s_add_u32 s82, s22, s32
	s_addc_u32 s83, s23, 0
	global_load_dwordx4 v[82:85], v134, s[28:29]
	global_load_dwordx4 v[86:89], v134, s[82:83]
	global_load_dwordx4 v[90:93], v135, s[28:29]
	global_load_dwordx4 v[94:97], v135, s[82:83]
.Lsb16_nost_1:
	s_and_b32 s38, s25, 63
	v_readlane_b32 s32, v133, s38
	v_readlane_b32 s38, v148, s38
	s_bitcmp1_b32 s25, 6
	s_cselect_b32 s76, s38, s32
	s_lshr_b32 s77, s76, 5
	s_add_i32 s77, s77, s97
	s_and_b32 s78, s76, 31
	v_readlane_b32 s79, v149, s77
	s_add_i32 s77, s77, 4
	v_readlane_b32 s80, v149, s77
	s_add_i32 s77, s77, 4
	v_readlane_b32 s81, v149, s77
	s_add_i32 s77, s77, 4
	v_readlane_b32 s82, v149, s77
	s_bitcmp1_b32 s79, s78
	s_cselect_b64 s[56:57], s[30:31], 0
	s_bitcmp1_b32 s80, s78
	s_cselect_b64 s[28:29], s[86:87], 0
	s_or_b64 s[56:57], s[56:57], s[28:29]
	s_bitcmp1_b32 s81, s78
	s_cselect_b64 s[98:99], s[30:31], 0
	s_bitcmp1_b32 s82, s78
	s_cselect_b64 s[28:29], s[86:87], 0
	s_or_b64 s[98:99], s[98:99], s[28:29]
	s_or_b64 s[28:29], s[56:57], s[98:99]
	s_cmp_eq_u64 s[28:29], 0
	s_cbranch_scc1 .Lsb16_end_1
	s_lshl_b32 s83, s76, 6
	v_subrev_u32_e32 v147, s83, v239
	s_cmp_eq_u64 s[56:57], 0
	s_cbranch_scc1 .Lsb16_g1_1
	ds_read_b128 v[50:53], v234 offset:18432
	ds_read_b128 v[54:57], v234 offset:18496
	ds_read_b128 v[58:61], v234 offset:20736
	ds_read_b128 v[62:65], v234 offset:20800
	v_cndmask_b32_e64 v146, v213, v100, s[56:57]
	s_waitcnt lgkmcnt(3)
	v_mfma_f32_16x16x32_bf16 v[34:37], v[50:53], v[66:69], 0
	s_waitcnt lgkmcnt(2)
	v_mfma_f32_16x16x32_bf16 v[34:37], v[54:57], v[70:73], v[34:37]
	ds_read_b128 v[50:53], v234 offset:23040
	ds_read_b128 v[54:57], v234 offset:23104
	s_waitcnt lgkmcnt(3)
	v_mfma_f32_16x16x32_bf16 v[38:41], v[58:61], v[66:69], 0
	s_waitcnt lgkmcnt(2)
	v_mfma_f32_16x16x32_bf16 v[38:41], v[62:65], v[70:73], v[38:41]
	ds_read_b128 v[58:61], v234 offset:25344
	ds_read_b128 v[62:65], v234 offset:25408
	s_waitcnt lgkmcnt(3)
	v_mfma_f32_16x16x32_bf16 v[42:45], v[50:53], v[66:69], 0
	s_waitcnt lgkmcnt(2)
	v_mfma_f32_16x16x32_bf16 v[42:45], v[54:57], v[70:73], v[42:45]
	s_waitcnt lgkmcnt(1)
	v_mfma_f32_16x16x32_bf16 v[46:49], v[58:61], v[66:69], 0
	s_waitcnt lgkmcnt(0)
	v_mfma_f32_16x16x32_bf16 v[46:49], v[62:65], v[70:73], v[46:49]
	ds_read_b128 v[50:53], v234 offset:27648
	ds_read_b128 v[54:57], v234 offset:27712
	ds_read_b128 v[58:61], v234 offset:29952
	ds_read_b128 v[62:65], v234 offset:30016
	v_fma_f32 v34, v34, s48, v146
	v_fma_f32 v35, v35, s48, v146
	v_fma_f32 v36, v36, s48, v146
	v_fma_f32 v37, v37, s48, v146
	v_fma_f32 v38, v38, s48, v146
	v_fma_f32 v39, v39, s48, v146
	v_fma_f32 v40, v40, s48, v146
	v_fma_f32 v41, v41, s48, v146
	v_fma_f32 v42, v42, s48, v146
	v_fma_f32 v43, v43, s48, v146
	v_fma_f32 v44, v44, s48, v146
	v_fma_f32 v45, v45, s48, v146
	v_fma_f32 v46, v46, s48, v146
	v_fma_f32 v47, v47, s48, v146
	v_fma_f32 v48, v48, s48, v146
	v_fma_f32 v49, v49, s48, v146
	s_cmp_lg_u32 s76, s72
	s_cbranch_scc1 .Lsb16_nm0_1
	v_cmp_le_i32_e64 s[28:29], 0, v147
	s_nop 1
	v_cndmask_b32_e64 v34, v213, v34, s[28:29]
	v_cmp_le_i32_e64 s[28:29], 1, v147
	s_nop 1
	v_cndmask_b32_e64 v35, v213, v35, s[28:29]
	v_cmp_le_i32_e64 s[28:29], 2, v147
	s_nop 1
	v_cndmask_b32_e64 v36, v213, v36, s[28:29]
	v_cmp_le_i32_e64 s[28:29], 3, v147
	s_nop 1
	v_cndmask_b32_e64 v37, v213, v37, s[28:29]
	v_cmp_le_i32_e64 s[28:29], 16, v147
	s_nop 1
	v_cndmask_b32_e64 v38, v213, v38, s[28:29]
	v_cmp_le_i32_e64 s[28:29], 17, v147
	s_nop 1
	v_cndmask_b32_e64 v39, v213, v39, s[28:29]
	v_cmp_le_i32_e64 s[28:29], 18, v147
	s_nop 1
	v_cndmask_b32_e64 v40, v213, v40, s[28:29]
	v_cmp_le_i32_e64 s[28:29], 19, v147
	s_nop 1
	v_cndmask_b32_e64 v41, v213, v41, s[28:29]
	v_cmp_le_i32_e64 s[28:29], 32, v147
	s_nop 1
	v_cndmask_b32_e64 v42, v213, v42, s[28:29]
	v_cmp_le_i32_e64 s[28:29], 33, v147
	s_nop 1
	v_cndmask_b32_e64 v43, v213, v43, s[28:29]
	v_cmp_le_i32_e64 s[28:29], 34, v147
	s_nop 1
	v_cndmask_b32_e64 v44, v213, v44, s[28:29]
	v_cmp_le_i32_e64 s[28:29], 35, v147
	s_nop 1
	v_cndmask_b32_e64 v45, v213, v45, s[28:29]
	v_cmp_le_i32_e64 s[28:29], 48, v147
	s_nop 1
	v_cndmask_b32_e64 v46, v213, v46, s[28:29]
	v_cmp_le_i32_e64 s[28:29], 49, v147
	s_nop 1
	v_cndmask_b32_e64 v47, v213, v47, s[28:29]
	v_cmp_le_i32_e64 s[28:29], 50, v147
	s_nop 1
	v_cndmask_b32_e64 v48, v213, v48, s[28:29]
	v_cmp_le_i32_e64 s[28:29], 51, v147
	s_nop 1
	v_cndmask_b32_e64 v49, v213, v49, s[28:29]
.Lsb16_nm0_1:
	v_exp_f32_e32 v34, v34
	v_exp_f32_e32 v35, v35
	v_exp_f32_e32 v36, v36
	v_exp_f32_e32 v37, v37
	v_exp_f32_e32 v38, v38
	v_exp_f32_e32 v39, v39
	v_exp_f32_e32 v40, v40
	v_exp_f32_e32 v41, v41
	v_exp_f32_e32 v42, v42
	v_exp_f32_e32 v43, v43
	v_exp_f32_e32 v44, v44
	v_exp_f32_e32 v45, v45
	v_exp_f32_e32 v46, v46
	v_exp_f32_e32 v47, v47
	v_exp_f32_e32 v48, v48
	v_exp_f32_e32 v49, v49
	v_add_f32_e32 v138, v34, v35
	v_add_f32_e32 v139, v36, v37
	v_add_f32_e32 v140, v38, v39
	v_add_f32_e32 v141, v40, v41
	v_add_f32_e32 v138, v138, v42
	v_add_f32_e32 v139, v139, v43
	v_add_f32_e32 v140, v140, v44
	v_add_f32_e32 v141, v141, v45
	v_add_f32_e32 v138, v138, v46
	v_add_f32_e32 v139, v139, v47
	v_add_f32_e32 v140, v140, v48
	v_add_f32_e32 v141, v141, v49
	v_add_f32_e32 v138, v138, v139
	v_add_f32_e32 v140, v140, v141
	v_add_f32_e32 v138, v138, v140
	v_add_f32_e32 v129, v129, v138
	v_cvt_pk_bf16_f32 v138, v34, v35
	v_cvt_pk_bf16_f32 v139, v36, v37
	v_cvt_pk_bf16_f32 v140, v38, v39
	v_cvt_pk_bf16_f32 v141, v40, v41
	v_cvt_pk_bf16_f32 v142, v42, v43
	v_cvt_pk_bf16_f32 v143, v44, v45
	v_cvt_pk_bf16_f32 v144, v46, v47
	v_cvt_pk_bf16_f32 v145, v48, v49
	s_waitcnt lgkmcnt(3)
	v_mfma_f32_16x16x32_bf16 v[2:5], v[50:53], v[138:141], v[2:5]
	s_waitcnt lgkmcnt(2)
	v_mfma_f32_16x16x32_bf16 v[2:5], v[54:57], v[142:145], v[2:5]
	ds_read_b128 v[50:53], v234 offset:32256
	ds_read_b128 v[54:57], v234 offset:32320
	s_waitcnt lgkmcnt(3)
	v_mfma_f32_16x16x32_bf16 v[6:9], v[58:61], v[138:141], v[6:9]
	s_waitcnt lgkmcnt(2)
	v_mfma_f32_16x16x32_bf16 v[6:9], v[62:65], v[142:145], v[6:9]
	ds_read_b128 v[58:61], v234 offset:34560
	ds_read_b128 v[62:65], v234 offset:34624
	s_waitcnt lgkmcnt(3)
	v_mfma_f32_16x16x32_bf16 v[10:13], v[50:53], v[138:141], v[10:13]
	s_waitcnt lgkmcnt(2)
	v_mfma_f32_16x16x32_bf16 v[10:13], v[54:57], v[142:145], v[10:13]
	s_waitcnt lgkmcnt(1)
	v_mfma_f32_16x16x32_bf16 v[14:17], v[58:61], v[138:141], v[14:17]
	s_waitcnt lgkmcnt(0)
	v_mfma_f32_16x16x32_bf16 v[14:17], v[62:65], v[142:145], v[14:17]
.Lsb16_g1_1:
	s_cmp_eq_u64 s[98:99], 0
	s_cbranch_scc1 .Lsb16_end_1
	ds_read_b128 v[50:53], v234 offset:18432
	ds_read_b128 v[54:57], v234 offset:18496
	ds_read_b128 v[58:61], v234 offset:20736
	ds_read_b128 v[62:65], v234 offset:20800
	v_cndmask_b32_e64 v146, v213, v100, s[98:99]
	v_add_u32_e32 v147, 2, v147
	s_waitcnt lgkmcnt(3)
	v_mfma_f32_16x16x32_bf16 v[34:37], v[50:53], v[74:77], 0
	s_waitcnt lgkmcnt(2)
	v_mfma_f32_16x16x32_bf16 v[34:37], v[54:57], v[78:81], v[34:37]
	ds_read_b128 v[50:53], v234 offset:23040
	ds_read_b128 v[54:57], v234 offset:23104
	s_waitcnt lgkmcnt(3)
	v_mfma_f32_16x16x32_bf16 v[38:41], v[58:61], v[74:77], 0
	s_waitcnt lgkmcnt(2)
	v_mfma_f32_16x16x32_bf16 v[38:41], v[62:65], v[78:81], v[38:41]
	ds_read_b128 v[58:61], v234 offset:25344
	ds_read_b128 v[62:65], v234 offset:25408
	s_waitcnt lgkmcnt(3)
	v_mfma_f32_16x16x32_bf16 v[42:45], v[50:53], v[74:77], 0
	s_waitcnt lgkmcnt(2)
	v_mfma_f32_16x16x32_bf16 v[42:45], v[54:57], v[78:81], v[42:45]
	s_waitcnt lgkmcnt(1)
	v_mfma_f32_16x16x32_bf16 v[46:49], v[58:61], v[74:77], 0
	s_waitcnt lgkmcnt(0)
	v_mfma_f32_16x16x32_bf16 v[46:49], v[62:65], v[78:81], v[46:49]
	ds_read_b128 v[50:53], v234 offset:27648
	ds_read_b128 v[54:57], v234 offset:27712
	ds_read_b128 v[58:61], v234 offset:29952
	ds_read_b128 v[62:65], v234 offset:30016
	v_fma_f32 v34, v34, s48, v146
	v_fma_f32 v35, v35, s48, v146
	v_fma_f32 v36, v36, s48, v146
	v_fma_f32 v37, v37, s48, v146
	v_fma_f32 v38, v38, s48, v146
	v_fma_f32 v39, v39, s48, v146
	v_fma_f32 v40, v40, s48, v146
	v_fma_f32 v41, v41, s48, v146
	v_fma_f32 v42, v42, s48, v146
	v_fma_f32 v43, v43, s48, v146
	v_fma_f32 v44, v44, s48, v146
	v_fma_f32 v45, v45, s48, v146
	v_fma_f32 v46, v46, s48, v146
	v_fma_f32 v47, v47, s48, v146
	v_fma_f32 v48, v48, s48, v146
	v_fma_f32 v49, v49, s48, v146
	s_cmp_lg_u32 s76, s72
	s_cbranch_scc1 .Lsb16_nm1_1
	v_cmp_le_i32_e64 s[28:29], 0, v147
	s_nop 1
	v_cndmask_b32_e64 v34, v213, v34, s[28:29]
	v_cmp_le_i32_e64 s[28:29], 1, v147
	s_nop 1
	v_cndmask_b32_e64 v35, v213, v35, s[28:29]
	v_cmp_le_i32_e64 s[28:29], 2, v147
	s_nop 1
	v_cndmask_b32_e64 v36, v213, v36, s[28:29]
	v_cmp_le_i32_e64 s[28:29], 3, v147
	s_nop 1
	v_cndmask_b32_e64 v37, v213, v37, s[28:29]
	v_cmp_le_i32_e64 s[28:29], 16, v147
	s_nop 1
	v_cndmask_b32_e64 v38, v213, v38, s[28:29]
	v_cmp_le_i32_e64 s[28:29], 17, v147
	s_nop 1
	v_cndmask_b32_e64 v39, v213, v39, s[28:29]
	v_cmp_le_i32_e64 s[28:29], 18, v147
	s_nop 1
	v_cndmask_b32_e64 v40, v213, v40, s[28:29]
	v_cmp_le_i32_e64 s[28:29], 19, v147
	s_nop 1
	v_cndmask_b32_e64 v41, v213, v41, s[28:29]
	v_cmp_le_i32_e64 s[28:29], 32, v147
	s_nop 1
	v_cndmask_b32_e64 v42, v213, v42, s[28:29]
	v_cmp_le_i32_e64 s[28:29], 33, v147
	s_nop 1
	v_cndmask_b32_e64 v43, v213, v43, s[28:29]
	v_cmp_le_i32_e64 s[28:29], 34, v147
	s_nop 1
	v_cndmask_b32_e64 v44, v213, v44, s[28:29]
	v_cmp_le_i32_e64 s[28:29], 35, v147
	s_nop 1
	v_cndmask_b32_e64 v45, v213, v45, s[28:29]
	v_cmp_le_i32_e64 s[28:29], 48, v147
	s_nop 1
	v_cndmask_b32_e64 v46, v213, v46, s[28:29]
	v_cmp_le_i32_e64 s[28:29], 49, v147
	s_nop 1
	v_cndmask_b32_e64 v47, v213, v47, s[28:29]
	v_cmp_le_i32_e64 s[28:29], 50, v147
	s_nop 1
	v_cndmask_b32_e64 v48, v213, v48, s[28:29]
	v_cmp_le_i32_e64 s[28:29], 51, v147
	s_nop 1
	v_cndmask_b32_e64 v49, v213, v49, s[28:29]
.Lsb16_nm1_1:
	v_exp_f32_e32 v34, v34
	v_exp_f32_e32 v35, v35
	v_exp_f32_e32 v36, v36
	v_exp_f32_e32 v37, v37
	v_exp_f32_e32 v38, v38
	v_exp_f32_e32 v39, v39
	v_exp_f32_e32 v40, v40
	v_exp_f32_e32 v41, v41
	v_exp_f32_e32 v42, v42
	v_exp_f32_e32 v43, v43
	v_exp_f32_e32 v44, v44
	v_exp_f32_e32 v45, v45
	v_exp_f32_e32 v46, v46
	v_exp_f32_e32 v47, v47
	v_exp_f32_e32 v48, v48
	v_exp_f32_e32 v49, v49
	v_add_f32_e32 v138, v34, v35
	v_add_f32_e32 v139, v36, v37
	v_add_f32_e32 v140, v38, v39
	v_add_f32_e32 v141, v40, v41
	v_add_f32_e32 v138, v138, v42
	v_add_f32_e32 v139, v139, v43
	v_add_f32_e32 v140, v140, v44
	v_add_f32_e32 v141, v141, v45
	v_add_f32_e32 v138, v138, v46
	v_add_f32_e32 v139, v139, v47
	v_add_f32_e32 v140, v140, v48
	v_add_f32_e32 v141, v141, v49
	v_add_f32_e32 v138, v138, v139
	v_add_f32_e32 v140, v140, v141
	v_add_f32_e32 v138, v138, v140
	v_add_f32_e32 v235, v235, v138
	v_cvt_pk_bf16_f32 v138, v34, v35
	v_cvt_pk_bf16_f32 v139, v36, v37
	v_cvt_pk_bf16_f32 v140, v38, v39
	v_cvt_pk_bf16_f32 v141, v40, v41
	v_cvt_pk_bf16_f32 v142, v42, v43
	v_cvt_pk_bf16_f32 v143, v44, v45
	v_cvt_pk_bf16_f32 v144, v46, v47
	v_cvt_pk_bf16_f32 v145, v48, v49
	s_waitcnt lgkmcnt(3)
	v_mfma_f32_16x16x32_bf16 v[18:21], v[50:53], v[138:141], v[18:21]
	s_waitcnt lgkmcnt(2)
	v_mfma_f32_16x16x32_bf16 v[18:21], v[54:57], v[142:145], v[18:21]
	ds_read_b128 v[50:53], v234 offset:32256
	ds_read_b128 v[54:57], v234 offset:32320
	s_waitcnt lgkmcnt(3)
	v_mfma_f32_16x16x32_bf16 v[22:25], v[58:61], v[138:141], v[22:25]
	s_waitcnt lgkmcnt(2)
	v_mfma_f32_16x16x32_bf16 v[22:25], v[62:65], v[142:145], v[22:25]
	ds_read_b128 v[58:61], v234 offset:34560
	ds_read_b128 v[62:65], v234 offset:34624
	s_waitcnt lgkmcnt(3)
	v_mfma_f32_16x16x32_bf16 v[26:29], v[50:53], v[138:141], v[26:29]
	s_waitcnt lgkmcnt(2)
	v_mfma_f32_16x16x32_bf16 v[26:29], v[54:57], v[142:145], v[26:29]
	s_waitcnt lgkmcnt(1)
	v_mfma_f32_16x16x32_bf16 v[30:33], v[58:61], v[138:141], v[30:33]
	s_waitcnt lgkmcnt(0)
	v_mfma_f32_16x16x32_bf16 v[30:33], v[62:65], v[142:145], v[30:33]
.Lsb16_end_1:
	s_add_i32 s25, s25, 1
	s_cmp_eq_u32 s25, s101
	s_waitcnt lgkmcnt(0)
	s_barrier
	s_cbranch_scc1 .LBB0_2180
	s_branch .Lsb16_step_0
